# w_in GEMM epilogue rewritten straight-line: masks and base address once per tile, permlane16_swap pairs -> one dwordx4 + one dwordx2 store per row group instead of 3 exec-masked dwordx2 branches
# speedup vs baseline: 1.0081x; 1.0081x over previous
.LBB0_309:
	s_add_i32 s45, s45, 2
	s_cmp_lg_u32 s45, 16
	s_waitcnt lgkmcnt(0)
	s_mov_b32 s98, 1
	s_cbranch_scc1 .LBB0_284
	s_mov_b32 s98, 0
	v_mfma_f32_16x16x32_bf16 v[78:81], v[170:173], v[142:145], v[78:81]
	v_mfma_f32_16x16x32_bf16 v[74:77], v[174:177], v[142:145], v[74:77]
	v_mfma_f32_16x16x32_bf16 v[70:73], v[178:181], v[142:145], v[70:73]
	v_mfma_f32_16x16x32_bf16 v[66:69], v[170:173], v[146:149], v[66:69]
	v_mfma_f32_16x16x32_bf16 v[62:65], v[174:177], v[146:149], v[62:65]
	v_mfma_f32_16x16x32_bf16 v[58:61], v[178:181], v[146:149], v[58:61]
	v_mfma_f32_16x16x32_bf16 v[50:53], v[170:173], v[150:153], v[50:53]
	v_mfma_f32_16x16x32_bf16 v[46:49], v[174:177], v[150:153], v[46:49]
	v_mfma_f32_16x16x32_bf16 v[42:45], v[178:181], v[150:153], v[42:45]
	v_mfma_f32_16x16x32_bf16 v[38:41], v[170:173], v[154:157], v[38:41]
	v_mfma_f32_16x16x32_bf16 v[34:37], v[174:177], v[154:157], v[34:37]
	v_mfma_f32_16x16x32_bf16 v[30:33], v[178:181], v[154:157], v[30:33]
	s_nop 7
	s_nop 7
	v_mov_b32_e32 v127, v0
	s_mul_i32 s2, s29, 0xc0
	s_nop 0
	v_lshrrev_b32_e32 v128, 2, v127
	v_bfe_u32 v126, v127, 6, 2
	v_and_or_b32 v128, v128, 12, s2
	v_mad_u32_u24 v126, v126, 48, v128
	v_ashrrev_i32_e32 v128, 1, v127
	v_and_b32_e32 v128, 0xffffff80, v128
	v_lshl_add_u32 v128, s31, 8, v128
	v_and_or_b32 v128, v127, 15, v128
	v_cmp_gt_i32_e32 vcc, s40, v126
	v_ashrrev_i32_e32 v127, 31, v126
	v_add_u32_e32 v134, 16, v126
	v_cmp_gt_i32_e64 s[2:3], s40, v134
	v_add_u32_e32 v134, 32, v126
	v_cmp_gt_i32_e64 s[4:5], s40, v134
	s_mov_b32 s14, 0xffff
	s_mov_b32 s15, 0xffff
	s_and_b64 s[20:21], vcc, s[14:15]
	s_andn2_b64 s[2:3], s[2:3], s[14:15]
	s_or_b64 s[20:21], s[20:21], s[2:3]
	s_lshl_b32 s14, s41, 4
	s_mov_b32 s15, 0
	v_mov_b64_e32 v[130:131], s[8:9]
	v_mad_i64_i32 v[130:131], s[2:3], v128, s41, v[130:131]
	v_lshl_add_u64 v[130:131], v[126:127], 1, v[130:131]
	v_bfe_u32 v134, v0, 4, 1
	v_mul_u32_u24_e32 v134, 24, v134
	v_mov_b32_e32 v135, 0
	v_lshl_add_u64 v[132:133], v[130:131], 0, v[134:135]
	v_cvt_pk_bf16_f32 v122, v122, v123
	v_cvt_pk_bf16_f32 v123, v124, v125
	v_cvt_pk_bf16_f32 v124, v118, v119
	v_cvt_pk_bf16_f32 v125, v120, v121
	v_cvt_pk_bf16_f32 v114, v114, v115
	v_cvt_pk_bf16_f32 v115, v116, v117
	s_nop 1
	v_permlane16_swap_b32_e32 v122, v124
	v_permlane16_swap_b32_e32 v123, v125
	s_mov_b64 exec, s[20:21]
	global_store_dwordx4 v[132:133], v[122:125], off
	s_mov_b64 exec, s[4:5]
	global_store_dwordx2 v[130:131], v[114:115], off offset:64
	s_mov_b64 exec, -1
	v_lshl_add_u64 v[130:131], v[130:131], 0, s[14:15]
	v_lshl_add_u64 v[132:133], v[132:133], 0, s[14:15]
	v_cvt_pk_bf16_f32 v110, v110, v111
	v_cvt_pk_bf16_f32 v111, v112, v113
	v_cvt_pk_bf16_f32 v112, v106, v107
	v_cvt_pk_bf16_f32 v113, v108, v109
	v_cvt_pk_bf16_f32 v102, v102, v103
	v_cvt_pk_bf16_f32 v103, v104, v105
	s_nop 1
	v_permlane16_swap_b32_e32 v110, v112
	v_permlane16_swap_b32_e32 v111, v113
	s_mov_b64 exec, s[20:21]
	global_store_dwordx4 v[132:133], v[110:113], off
	s_mov_b64 exec, s[4:5]
	global_store_dwordx2 v[130:131], v[102:103], off offset:64
	s_mov_b64 exec, -1
	v_lshl_add_u64 v[130:131], v[130:131], 0, s[14:15]
	v_lshl_add_u64 v[132:133], v[132:133], 0, s[14:15]
	v_cvt_pk_bf16_f32 v98, v98, v99
	v_cvt_pk_bf16_f32 v99, v100, v101
	v_cvt_pk_bf16_f32 v100, v94, v95
	v_cvt_pk_bf16_f32 v101, v96, v97
	v_cvt_pk_bf16_f32 v90, v90, v91
	v_cvt_pk_bf16_f32 v91, v92, v93
	s_nop 1
	v_permlane16_swap_b32_e32 v98, v100
	v_permlane16_swap_b32_e32 v99, v101
	s_mov_b64 exec, s[20:21]
	global_store_dwordx4 v[132:133], v[98:101], off
	s_mov_b64 exec, s[4:5]
	global_store_dwordx2 v[130:131], v[90:91], off offset:64
	s_mov_b64 exec, -1
	v_lshl_add_u64 v[130:131], v[130:131], 0, s[14:15]
	v_lshl_add_u64 v[132:133], v[132:133], 0, s[14:15]
	v_cvt_pk_bf16_f32 v86, v86, v87
	v_cvt_pk_bf16_f32 v87, v88, v89
	v_cvt_pk_bf16_f32 v88, v82, v83
	v_cvt_pk_bf16_f32 v89, v84, v85
	v_cvt_pk_bf16_f32 v54, v54, v55
	v_cvt_pk_bf16_f32 v55, v56, v57
	s_nop 1
	v_permlane16_swap_b32_e32 v86, v88
	v_permlane16_swap_b32_e32 v87, v89
	s_mov_b64 exec, s[20:21]
	global_store_dwordx4 v[132:133], v[86:89], off
	s_mov_b64 exec, s[4:5]
	global_store_dwordx2 v[130:131], v[54:55], off offset:64
	s_mov_b64 exec, -1
	v_lshl_add_u64 v[130:131], v[130:131], 0, s[14:15]
	v_lshl_add_u64 v[132:133], v[132:133], 0, s[14:15]
	v_cvt_pk_bf16_f32 v78, v78, v79
	v_cvt_pk_bf16_f32 v79, v80, v81
	v_cvt_pk_bf16_f32 v80, v74, v75
	v_cvt_pk_bf16_f32 v81, v76, v77
	v_cvt_pk_bf16_f32 v70, v70, v71
	v_cvt_pk_bf16_f32 v71, v72, v73
	s_nop 1
	v_permlane16_swap_b32_e32 v78, v80
	v_permlane16_swap_b32_e32 v79, v81
	s_mov_b64 exec, s[20:21]
	global_store_dwordx4 v[132:133], v[78:81], off
	s_mov_b64 exec, s[4:5]
	global_store_dwordx2 v[130:131], v[70:71], off offset:64
	s_mov_b64 exec, -1
	v_lshl_add_u64 v[130:131], v[130:131], 0, s[14:15]
	v_lshl_add_u64 v[132:133], v[132:133], 0, s[14:15]
	v_cvt_pk_bf16_f32 v66, v66, v67
	v_cvt_pk_bf16_f32 v67, v68, v69
	v_cvt_pk_bf16_f32 v68, v62, v63
	v_cvt_pk_bf16_f32 v69, v64, v65
	v_cvt_pk_bf16_f32 v58, v58, v59
	v_cvt_pk_bf16_f32 v59, v60, v61
	s_nop 1
	v_permlane16_swap_b32_e32 v66, v68
	v_permlane16_swap_b32_e32 v67, v69
	s_mov_b64 exec, s[20:21]
	global_store_dwordx4 v[132:133], v[66:69], off
	s_mov_b64 exec, s[4:5]
	global_store_dwordx2 v[130:131], v[58:59], off offset:64
	s_mov_b64 exec, -1
	v_lshl_add_u64 v[130:131], v[130:131], 0, s[14:15]
	v_lshl_add_u64 v[132:133], v[132:133], 0, s[14:15]
	v_cvt_pk_bf16_f32 v50, v50, v51
	v_cvt_pk_bf16_f32 v51, v52, v53
	v_cvt_pk_bf16_f32 v52, v46, v47
	v_cvt_pk_bf16_f32 v53, v48, v49
	v_cvt_pk_bf16_f32 v42, v42, v43
	v_cvt_pk_bf16_f32 v43, v44, v45
	s_nop 1
	v_permlane16_swap_b32_e32 v50, v52
	v_permlane16_swap_b32_e32 v51, v53
	s_mov_b64 exec, s[20:21]
	global_store_dwordx4 v[132:133], v[50:53], off
	s_mov_b64 exec, s[4:5]
	global_store_dwordx2 v[130:131], v[42:43], off offset:64
	s_mov_b64 exec, -1
	v_lshl_add_u64 v[130:131], v[130:131], 0, s[14:15]
	v_lshl_add_u64 v[132:133], v[132:133], 0, s[14:15]
	v_cvt_pk_bf16_f32 v38, v38, v39
	v_cvt_pk_bf16_f32 v39, v40, v41
	v_cvt_pk_bf16_f32 v40, v34, v35
	v_cvt_pk_bf16_f32 v41, v36, v37
	v_cvt_pk_bf16_f32 v30, v30, v31
	v_cvt_pk_bf16_f32 v31, v32, v33
	s_nop 1
	v_permlane16_swap_b32_e32 v38, v40
	v_permlane16_swap_b32_e32 v39, v41
	s_mov_b64 exec, s[20:21]
	global_store_dwordx4 v[132:133], v[38:41], off
	s_mov_b64 exec, s[4:5]
	global_store_dwordx2 v[130:131], v[30:31], off offset:64
	s_mov_b64 exec, -1
	s_mov_b64 s[2:3], exec
	s_branch .LBB0_337
.LBB0_312:
.LBB0_314:
.LBB0_316:
.LBB0_317:
.LBB0_318:
.LBB0_319:
.LBB0_320:
.LBB0_321:
.LBB0_322:
.LBB0_323:
.LBB0_324:
.LBB0_325:
.LBB0_326:
.LBB0_327:
.LBB0_328:
.LBB0_329:
.LBB0_330:
.LBB0_331:
.LBB0_332:
.LBB0_333:
.LBB0_334:
.LBB0_335:
.LBB0_336:
.LBB0_337:
	s_or_b64 exec, exec, s[2:3]
	s_add_i32 s42, s42, s11
	v_mov_b32_e32 v33, 0
	s_cmpk_gt_i32 s42, 0x5f
	s_cbranch_scc1 .LBB0_283
	s_ashr_i32 s3, s42, 31
	s_lshr_b32 s3, s3, 27
	s_add_i32 s3, s42, s3
	s_ashr_i32 s3, s3, 5
	s_mov_b32 s2, s10
	s_lshl_b32 s4, s3, 6
	s_lshl_b32 s5, s42, 1
	s_sub_i32 s4, s5, s4
	s_and_b32 s2, s2, 7
	s_and_b32 s4, s4, -8
	s_lshl_b32 s3, s3, 2
	s_and_b32 s5, s42, 3
	s_or_b32 s29, s3, s5
	s_or_b32 s31, s2, s4
	s_branch .LBB0_283
.LBB0_339:
.LBB0_340:
.LBB0_341:
.LBB0_342:
.LBB0_343:
.LBB0_344:
.LBB0_345:
.LBB0_346:
.LBB0_347:
.LBB0_348:
.LBB0_349:
.LBB0_350:
.LBB0_351:
.LBB0_352:
.LBB0_353:
.LBB0_354:
.LBB0_355:
.LBB0_356:
.LBB0_357:
.LBB0_358:
.LBB0_359:
	s_branch .LBB0_337
